# v12 + per-CU start stagger (bx/256 of a 3-6 us window) at the P1/P7/P9/P10 GEMM phase entries so epilogue store bursts interleave
# speedup vs baseline: 1.0017x; 1.0017x over previous
.LBB0_80:
	s_load_dwordx2 s[2:3], s[82:83], 0x118
	s_load_dwordx2 s[4:5], s[82:83], 0x90
	s_waitcnt lgkmcnt(0)
	s_cmp_lt_i32 s2, 2
	s_cselect_b64 s[2:3], -1, 0
	s_add_u32 s4, s4, 0x2fe00000
	s_addc_u32 s5, s5, 0
	s_and_b64 s[0:1], s[2:3], s[0:1]
	v_writelane_b32 v245, s4, 17
	s_andn2_b64 vcc, exec, s[0:1]
	s_nop 0
	v_writelane_b32 v245, s5, 18
	s_cbranch_vccnz .LBB0_115
	s_cmpk_gt_i32 s81, 0x10ff
	v_readfirstlane_b32 s5, v0
	s_cbranch_scc1 .LBB0_115
	s_memrealtime s[98:99]
	s_and_b32 s100, s81, 0xff
	s_mulk_i32 s100, 0x280
	s_lshr_b32 s100, s100, 8
	s_waitcnt lgkmcnt(0)
	s_add_u32 s100, s98, s100
.Lstg_p1:
	s_memrealtime s[98:99]
	s_waitcnt lgkmcnt(0)
	s_sub_u32 s101, s100, s98
	s_cmp_gt_i32 s101, 0
	s_cbranch_scc1 .Lstg_p1
	s_load_dwordx2 s[2:3], s[82:83], 0x90
	v_lshrrev_b32_e32 v1, 5, v0
	v_lshrrev_b32_e32 v3, 1, v0
	v_and_b32_e32 v1, 4, v1
	v_bfe_u32 v2, v0, 2, 2
	v_and_b32_e32 v14, 24, v3
	v_or3_b32 v1, v1, v2, v14
	v_lshlrev_b32_e32 v2, 4, v0
	v_or_b32_e32 v10, 0x2000, v2
	s_waitcnt lgkmcnt(0)
	s_add_u32 s33, s2, 0x100000
	v_lshrrev_b32_e32 v3, 7, v10
	s_movk_i32 s2, 0x60
	s_addc_u32 s48, s3, 0
	v_and_or_b32 v4, v3, s2, v1
	v_bfe_u32 v13, v0, 2, 4
	s_movk_i32 s2, 0x70
	s_ashr_i32 s50, s81, 31
	v_and_or_b32 v3, v3, s2, v13
	s_lshr_b32 s2, s50, 29
	s_add_i32 s2, s81, s2
	s_lshr_b32 s10, s5, 6
	s_ashr_i32 s3, s2, 3
	s_and_b32 s2, s2, -8
	s_lshr_b32 s12, s5, 8
	s_lshl_b32 s49, s10, 10
	s_sub_i32 s2, s81, s2
	s_cmp_lt_i32 s2, 0
	s_movk_i32 s51, 0x221
	s_cselect_b32 s4, s51, 0x220
	s_mul_i32 s2, s2, s4
	s_add_i32 s2, s2, s3
	s_mul_hi_i32 s3, s2, 0x78787879
	s_lshr_b32 s4, s3, 31
	s_ashr_i32 s3, s3, 7
	s_add_i32 s3, s3, s4
	s_lshl_b32 s6, s3, 3
	s_mulk_i32 s3, 0x110
	s_sub_i32 s2, s2, s3
	s_sext_i32_i16 s3, s2
	s_bfe_u32 s3, s3, 0x3001c
	s_add_i32 s3, s2, s3
	s_sext_i32_i16 s4, s3
	s_and_b32 s3, s3, 0xfff8
	s_sub_i32 s2, s2, s3
	s_sext_i32_i16 s2, s2
	v_and_b32_e32 v5, 32, v0
	s_lshr_b32 s4, s4, 3
	s_add_i32 s38, s6, s2
	v_bitop3_b32 v11, v2, v5, 48 bitop3:0x6c
	v_and_b32_e32 v12, 64, v0
	s_ashr_i32 s39, s38, 31
	s_bfe_i64 s[6:7], s[4:5], 0x100000
	v_or_b32_e32 v2, v11, v12
	s_lshl_b64 s[2:3], s[38:39], 20
	s_lshl_b64 s[6:7], s[6:7], 20
	v_lshl_or_b32 v148, v3, 12, v2
	v_lshrrev_b32_e32 v3, 3, v0
	s_add_u32 s42, s33, s6
	v_and_or_b32 v1, v3, 32, v1
	s_addc_u32 s43, s48, s7
	s_add_i32 s52, s49, 0
	v_lshl_or_b32 v150, v1, 12, v2
	s_add_i32 m0, s52, 0x10000
	v_lshl_or_b32 v146, v4, 12, v2
	global_load_lds_dwordx4 v150, s[42:43]
	s_add_i32 m0, s52, 0x12000
	s_add_u32 s6, s42, 0x80000
	global_load_lds_dwordx4 v146, s[42:43]
	s_addc_u32 s7, s43, 0
	s_add_i32 m0, s52, 0x14000
	v_and_or_b32 v1, v3, 48, v13
	global_load_lds_dwordx4 v150, s[6:7]
	s_add_i32 m0, s52, 0x16000
	v_lshl_or_b32 v152, v1, 12, v2
	global_load_lds_dwordx4 v146, s[6:7]
	v_readlane_b32 s6, v245, 14
	v_readlane_b32 s7, v245, 15
	s_add_u32 s40, s6, s2
	s_addc_u32 s41, s7, s3
	s_add_i32 s53, s52, 0x2000
	s_mov_b32 m0, s52
	s_add_u32 s2, s40, 0x80000
	global_load_lds_dwordx4 v152, s[40:41]
	s_mov_b32 m0, s53
	s_addc_u32 s3, s41, 0
	s_add_i32 s54, s52, 0x4000
	global_load_lds_dwordx4 v148, s[40:41]
	s_mov_b32 m0, s54
	s_add_i32 s55, s52, 0x6000
	global_load_lds_dwordx4 v152, s[2:3]
	s_mov_b32 m0, s55
	v_mov_b32_e32 v155, 0
	global_load_lds_dwordx4 v148, s[2:3]
	v_mov_b32_e32 v151, v155
	v_mov_b32_e32 v147, v155
	v_mov_b32_e32 v153, v155
	v_mov_b32_e32 v149, v155
	s_cmp_eq_u32 s12, 1
	s_mov_b32 s56, 0
	v_lshl_add_u64 v[8:9], s[42:43], 0, v[150:151]
	v_lshl_add_u64 v[6:7], s[42:43], 0, v[146:147]
	v_lshl_add_u64 v[2:3], s[40:41], 0, v[152:153]
	s_cselect_b64 s[2:3], -1, 0
	s_cmp_lg_u32 s12, 1
	v_lshl_add_u64 v[4:5], s[40:41], 0, v[148:149]
	s_cbranch_scc1 .LBB0_84
	s_barrier

.LBB0_617:
	v_readlane_b32 s0, v245, 5
	v_readlane_b32 s1, v245, 6
	s_cmp_lt_i32 s0, 8
	s_cselect_b64 s[0:1], -1, 0
	s_and_b64 s[0:1], s[0:1], s[2:3]
	s_andn2_b64 vcc, exec, s[0:1]
	s_cbranch_vccnz .LBB0_642
	s_cmpk_gt_i32 s81, 0x3ff
	v_readfirstlane_b32 s5, v0
	s_cbranch_scc1 .LBB0_642
	s_memrealtime s[98:99]
	s_and_b32 s100, s81, 0xff
	s_mulk_i32 s100, 0x280
	s_lshr_b32 s100, s100, 8
	s_waitcnt lgkmcnt(0)
	s_add_u32 s100, s98, s100
.Lstg_p7:
	s_memrealtime s[98:99]
	s_waitcnt lgkmcnt(0)
	s_sub_u32 s101, s100, s98
	s_cmp_gt_i32 s101, 0
	s_cbranch_scc1 .Lstg_p7
	s_ashr_i32 s33, s81, 31
	s_lshr_b32 s2, s33, 29
	s_add_i32 s6, s81, s2
	s_and_b32 s2, s6, -8
	s_sub_i32 s7, s81, s2
	s_cmp_gt_i32 s7, -1
	s_cbranch_scc0 .LBB0_621
	s_lshl_b32 s4, s7, 7
	s_cbranch_execz .LBB0_622
	s_branch .LBB0_623

.LBB0_760:
	v_readlane_b32 s2, v245, 5
	v_readlane_b32 s3, v245, 6
	s_cmp_lt_i32 s2, 10
	s_cselect_b64 s[2:3], -1, 0
	s_and_b64 s[0:1], s[2:3], s[0:1]
	s_andn2_b64 vcc, exec, s[0:1]
	s_cbranch_vccnz .LBB0_777
	s_cmpk_gt_i32 s81, 0x15ff
	v_readfirstlane_b32 s5, v0
	s_cbranch_scc1 .LBB0_777
	s_memrealtime s[98:99]
	s_and_b32 s100, s81, 0xff
	s_mulk_i32 s100, 0x14a
	s_lshr_b32 s100, s100, 8
	s_waitcnt lgkmcnt(0)
	s_add_u32 s100, s98, s100
.Lstg_p9:
	s_memrealtime s[98:99]
	s_waitcnt lgkmcnt(0)
	s_sub_u32 s101, s100, s98
	s_cmp_gt_i32 s101, 0
	s_cbranch_scc1 .Lstg_p9
	s_load_dwordx2 s[2:3], s[82:83], 0x90
	v_lshrrev_b32_e32 v1, 5, v0
	v_lshrrev_b32_e32 v3, 1, v0
	v_and_b32_e32 v1, 4, v1
	v_bfe_u32 v2, v0, 2, 2
	v_and_b32_e32 v13, 24, v3
	v_or3_b32 v1, v1, v2, v13
	v_lshlrev_b32_e32 v2, 4, v0
	v_or_b32_e32 v10, 0x2000, v2
	s_waitcnt lgkmcnt(0)
	s_add_u32 s30, s2, 0x3740000
	v_lshrrev_b32_e32 v3, 7, v10
	s_movk_i32 s2, 0x60
	s_addc_u32 s31, s3, 0
	v_and_or_b32 v4, v3, s2, v1
	v_bfe_u32 v14, v0, 2, 4
	s_movk_i32 s2, 0x70
	s_ashr_i32 s34, s81, 31
	v_and_or_b32 v3, v3, s2, v14
	s_lshr_b32 s2, s34, 29
	s_add_i32 s2, s81, s2
	s_lshr_b32 s10, s5, 6
	s_ashr_i32 s3, s2, 3
	s_and_b32 s2, s2, -8
	s_lshr_b32 s12, s5, 8
	s_lshl_b32 s33, s10, 10
	s_sub_i32 s2, s81, s2
	s_cmp_lt_i32 s2, 0
	s_movk_i32 s35, 0x2c1
	s_cselect_b32 s4, s35, 0x2c0
	s_mul_i32 s2, s2, s4
	s_add_i32 s2, s2, s3
	s_mul_hi_i32 s3, s2, 0x2e8ba2e9
	s_lshr_b32 s4, s3, 31
	s_ashr_i32 s3, s3, 6
	s_add_i32 s3, s3, s4
	s_lshl_b32 s6, s3, 3
	s_mulk_i32 s3, 0x160
	s_sub_i32 s2, s2, s3
	s_sext_i32_i16 s3, s2
	s_bfe_u32 s3, s3, 0x3001c
	s_add_i32 s3, s2, s3
	s_sext_i32_i16 s4, s3
	s_and_b32 s3, s3, 0xfff8
	s_sub_i32 s2, s2, s3
	s_sext_i32_i16 s2, s2
	v_and_b32_e32 v5, 32, v0
	s_lshr_b32 s4, s4, 3
	s_add_i32 s22, s6, s2
	v_bitop3_b32 v11, v2, v5, 48 bitop3:0x6c
	v_and_b32_e32 v12, 64, v0
	s_ashr_i32 s23, s22, 31
	s_bfe_i64 s[6:7], s[4:5], 0x100000
	v_or_b32_e32 v2, v11, v12
	s_lshl_b64 s[2:3], s[22:23], 20
	s_lshl_b64 s[6:7], s[6:7], 20
	s_waitcnt vmcnt(0)
	v_lshl_or_b32 v132, v3, 12, v2
	v_lshrrev_b32_e32 v3, 3, v0
	s_add_u32 s26, s30, s6
	v_and_or_b32 v1, v3, 32, v1
	s_addc_u32 s27, s31, s7
	s_add_i32 s23, s33, 0
	v_lshl_or_b32 v134, v1, 12, v2
	s_add_i32 m0, s23, 0x10000
	v_lshl_or_b32 v130, v4, 12, v2
	global_load_lds_dwordx4 v134, s[26:27]
	s_add_i32 m0, s23, 0x12000
	s_add_u32 s6, s26, 0x80000
	global_load_lds_dwordx4 v130, s[26:27]
	s_addc_u32 s7, s27, 0
	s_add_i32 m0, s23, 0x14000
	v_and_or_b32 v1, v3, 48, v14
	global_load_lds_dwordx4 v134, s[6:7]
	s_add_i32 m0, s23, 0x16000
	v_lshl_or_b32 v136, v1, 12, v2
	global_load_lds_dwordx4 v130, s[6:7]
	v_readlane_b32 s6, v245, 17
	v_readlane_b32 s7, v245, 18
	s_add_u32 s24, s6, s2
	s_addc_u32 s25, s7, s3
	s_add_i32 s36, s23, 0x2000
	s_mov_b32 m0, s23
	s_add_u32 s2, s24, 0x80000
	global_load_lds_dwordx4 v136, s[24:25]
	s_mov_b32 m0, s36
	s_addc_u32 s3, s25, 0
	s_add_i32 s37, s23, 0x4000
	global_load_lds_dwordx4 v132, s[24:25]
	s_mov_b32 m0, s37
	s_add_i32 s38, s23, 0x6000
	global_load_lds_dwordx4 v136, s[2:3]
	s_mov_b32 m0, s38
	v_mov_b32_e32 v135, 0
	global_load_lds_dwordx4 v132, s[2:3]
	v_mov_b32_e32 v131, v135
	v_mov_b32_e32 v137, v135
	v_mov_b32_e32 v133, v135
	s_cmp_eq_u32 s12, 1
	s_mov_b32 s56, s42
	s_mov_b32 s39, 0
	v_lshl_add_u64 v[8:9], s[26:27], 0, v[134:135]
	v_lshl_add_u64 v[6:7], s[26:27], 0, v[130:131]
	v_lshl_add_u64 v[2:3], s[24:25], 0, v[136:137]
	s_cselect_b64 s[2:3], -1, 0
	s_cmp_lg_u32 s12, 1
	v_lshl_add_u64 v[4:5], s[24:25], 0, v[132:133]
	s_cbranch_scc1 .LBB0_764
	s_barrier

.LBB0_831:
	v_readlane_b32 s0, v245, 5
	v_readlane_b32 s1, v245, 6
	s_cmp_lt_i32 s0, 11
	s_cselect_b64 s[0:1], -1, 0
	s_and_b64 s[2:3], s[0:1], s[2:3]
	s_andn2_b64 vcc, exec, s[2:3]
	s_cbranch_vccnz .LBB0_860
	s_cmpk_gt_i32 s81, 0x3ff
	v_readfirstlane_b32 s4, v0
	s_cbranch_scc1 .LBB0_860
	s_memrealtime s[98:99]
	s_and_b32 s100, s81, 0xff
	s_mulk_i32 s100, 0x280
	s_lshr_b32 s100, s100, 8
	s_waitcnt lgkmcnt(0)
	s_add_u32 s100, s98, s100
.Lstg_p10:
	s_memrealtime s[98:99]
	s_waitcnt lgkmcnt(0)
	s_sub_u32 s101, s100, s98
	s_cmp_gt_i32 s101, 0
	s_cbranch_scc1 .Lstg_p10
	s_ashr_i32 s28, s81, 31
	s_lshr_b32 s0, s28, 29
	s_add_i32 s6, s81, s0
	s_and_b32 s0, s6, -8
	s_sub_i32 s7, s81, s0
	s_cmp_gt_i32 s7, -1
	s_cbranch_scc0 .LBB0_835
	s_lshl_b32 s5, s7, 7
	s_ashr_i32 s6, s6, 3
	s_cbranch_execz .LBB0_836
	s_branch .LBB0_837
